# attention epilogue: 16 dwordx2 row-per-lane stores become 8 dwordx4 via v_permlane32_swap; last three norm-weight loads hoisted; exact vmcnt recount
# speedup vs baseline: 1.0071x; 1.0071x over previous
.LBB0_527:
	ds_bpermute_b32 v16, v221, v193
	s_waitcnt lgkmcnt(0)
	s_barrier
	s_mov_b32 s15, 0x800000
	s_waitcnt lgkmcnt(0)
	v_add_f32_e32 v16, v193, v16
	v_div_scale_f32 v17, s[16:17], v16, v16, 1.0
	v_rcp_f32_e32 v18, v17
	v_div_scale_f32 v19, vcc, 1.0, v16, 1.0
	v_fma_f32 v20, -v17, v18, 1.0
	v_fmac_f32_e32 v18, v20, v18
	v_mul_f32_e32 v20, v19, v18
	v_fma_f32 v21, -v17, v20, v19
	v_fmac_f32_e32 v20, v21, v18
	v_fma_f32 v17, -v17, v20, v19
	v_div_fmas_f32 v17, v17, v18, v20
	v_div_fixup_f32 v20, v17, v16, 1.0
	v_cndmask_b32_e64 v16, 0, 1, s[6:7]
	v_cmp_ne_u32_e64 s[72:73], 1, v16
	s_andn2_b64 vcc, exec, s[6:7]
	s_mov_b64 s[6:7], -1
	s_cbranch_vccnz .LBB0_529
	ds_read2st64_b32 v[16:17], v209 offset0:224 offset1:225
	ds_read2st64_b32 v[18:19], v209 offset0:226 offset1:227
	ds_read2st64_b32 v[22:23], v209 offset0:228 offset1:229
	ds_read2st64_b32 v[24:25], v209 offset0:230 offset1:231
	v_pk_mul_f32 v[64:65], v[130:131], v[20:21] op_sel_hi:[1,0]
	s_waitcnt lgkmcnt(3)
	v_lshlrev_b32_e32 v36, 16, v16
	v_and_b32_e32 v37, 0xffff0000, v16
	v_lshlrev_b32_e32 v38, 16, v17
	v_and_b32_e32 v39, 0xffff0000, v17
	ds_read2st64_b32 v[16:17], v209 offset0:232 offset1:233
	s_waitcnt lgkmcnt(3)
	v_lshlrev_b32_e32 v40, 16, v18
	v_and_b32_e32 v41, 0xffff0000, v18
	v_lshlrev_b32_e32 v42, 16, v19
	v_and_b32_e32 v43, 0xffff0000, v19
	s_waitcnt lgkmcnt(2)
	v_lshlrev_b32_e32 v44, 16, v22
	v_and_b32_e32 v45, 0xffff0000, v22
	v_lshlrev_b32_e32 v46, 16, v23
	v_and_b32_e32 v47, 0xffff0000, v23
	s_waitcnt lgkmcnt(1)
	v_lshlrev_b32_e32 v48, 16, v24
	v_and_b32_e32 v49, 0xffff0000, v24
	v_lshlrev_b32_e32 v50, 16, v25
	v_and_b32_e32 v51, 0xffff0000, v25
	ds_read2st64_b32 v[18:19], v209 offset0:234 offset1:235
	ds_read2st64_b32 v[22:23], v209 offset0:236 offset1:237
	ds_read2st64_b32 v[24:25], v209 offset0:238 offset1:239
	s_waitcnt lgkmcnt(3)
	v_lshlrev_b32_e32 v52, 16, v16
	v_and_b32_e32 v53, 0xffff0000, v16
	v_lshlrev_b32_e32 v54, 16, v17
	v_and_b32_e32 v55, 0xffff0000, v17
	ds_read2st64_b32 v[16:17], v209 offset0:240 offset1:241
	s_waitcnt lgkmcnt(3)
	v_lshlrev_b32_e32 v56, 16, v18
	v_and_b32_e32 v57, 0xffff0000, v18
	v_lshlrev_b32_e32 v58, 16, v19
	v_and_b32_e32 v59, 0xffff0000, v19
	s_waitcnt lgkmcnt(2)
	v_lshlrev_b32_e32 v62, 16, v22
	v_and_b32_e32 v63, 0xffff0000, v22
	v_lshlrev_b32_e32 v60, 16, v23
	v_and_b32_e32 v61, 0xffff0000, v23
	s_waitcnt lgkmcnt(1)
	v_lshlrev_b32_e32 v156, 16, v24
	v_and_b32_e32 v157, 0xffff0000, v24
	v_lshlrev_b32_e32 v158, 16, v25
	v_and_b32_e32 v159, 0xffff0000, v25
	ds_read2st64_b32 v[18:19], v209 offset0:242 offset1:243
	ds_read2st64_b32 v[22:23], v209 offset0:244 offset1:245
	ds_read2st64_b32 v[24:25], v209 offset0:246 offset1:247
	s_waitcnt lgkmcnt(3)
	v_lshlrev_b32_e32 v160, 16, v16
	v_and_b32_e32 v161, 0xffff0000, v16
	v_lshlrev_b32_e32 v162, 16, v17
	v_and_b32_e32 v163, 0xffff0000, v17
	ds_read2st64_b32 v[16:17], v209 offset0:248 offset1:249
	s_waitcnt lgkmcnt(3)
	v_lshlrev_b32_e32 v164, 16, v18
	v_and_b32_e32 v165, 0xffff0000, v18
	v_lshlrev_b32_e32 v166, 16, v19
	v_and_b32_e32 v167, 0xffff0000, v19
	s_waitcnt lgkmcnt(2)
	v_lshlrev_b32_e32 v168, 16, v22
	v_and_b32_e32 v169, 0xffff0000, v22
	v_lshlrev_b32_e32 v170, 16, v23
	v_and_b32_e32 v171, 0xffff0000, v23
	s_waitcnt lgkmcnt(1)
	v_lshlrev_b32_e32 v30, 16, v24
	v_and_b32_e32 v31, 0xffff0000, v24
	v_lshlrev_b32_e32 v192, 16, v25
	v_and_b32_e32 v193, 0xffff0000, v25
	ds_read2st64_b32 v[18:19], v209 offset0:250 offset1:251
	ds_read2st64_b32 v[22:23], v209 offset0:252 offset1:253
	ds_read2st64_b32 v[24:25], v209 offset0:254 offset1:255
	s_waitcnt lgkmcnt(3)
	v_lshlrev_b32_e32 v222, 16, v16
	v_and_b32_e32 v223, 0xffff0000, v16
	s_waitcnt lgkmcnt(2)
	v_lshlrev_b32_e32 v34, 16, v18
	v_and_b32_e32 v35, 0xffff0000, v18
	v_lshlrev_b32_e32 v226, 16, v19
	v_and_b32_e32 v227, 0xffff0000, v19
	v_mov_b32_e32 v18, v88
	v_mov_b32_e32 v19, v90
	v_lshlrev_b32_e32 v224, 16, v17
	v_and_b32_e32 v225, 0xffff0000, v17
	s_waitcnt lgkmcnt(1)
	v_lshlrev_b32_e32 v17, 16, v23
	v_lshlrev_b32_e32 v16, 16, v22
	v_pk_mul_f32 v[18:19], v[18:19], v[20:21] op_sel_hi:[1,0]
	v_pk_fma_f32 v[76:77], v[178:179], v[64:65], v[38:39] neg_lo:[1,0,0] neg_hi:[1,0,0]
	v_pk_fma_f32 v[26:27], v[178:179], v[18:19], v[16:17] neg_lo:[1,0,0] neg_hi:[1,0,0]
	v_mov_b32_e32 v18, v89
	v_mov_b32_e32 v19, v91
	v_and_b32_e32 v17, 0xffff0000, v23
	v_and_b32_e32 v16, 0xffff0000, v22
	v_pk_mul_f32 v[18:19], v[18:19], v[20:21] op_sel_hi:[1,0]
	v_pk_mul_f32 v[38:39], v[128:129], v[20:21] op_sel_hi:[1,0]
	v_pk_fma_f32 v[28:29], v[178:179], v[18:19], v[16:17] neg_lo:[1,0,0] neg_hi:[1,0,0]
	v_mov_b32_e32 v18, v92
	v_pk_mul_f32 v[16:17], v[28:29], v[28:29]
	v_mov_b32_e32 v19, v94
	v_pk_fma_f32 v[32:33], v[26:27], v[26:27], v[16:17]
	s_waitcnt lgkmcnt(0)
	v_lshlrev_b32_e32 v17, 16, v25
	v_lshlrev_b32_e32 v16, 16, v24
	v_pk_mul_f32 v[18:19], v[18:19], v[20:21] op_sel_hi:[1,0]
	v_pk_fma_f32 v[148:149], v[178:179], v[38:39], v[36:37] neg_lo:[1,0,0] neg_hi:[1,0,0]
	v_pk_fma_f32 v[22:23], v[178:179], v[18:19], v[16:17] neg_lo:[1,0,0] neg_hi:[1,0,0]
	v_mov_b32_e32 v18, v93
	v_mov_b32_e32 v19, v95
	v_and_b32_e32 v17, 0xffff0000, v25
	v_and_b32_e32 v16, 0xffff0000, v24
	v_pk_mul_f32 v[18:19], v[18:19], v[20:21] op_sel_hi:[1,0]
	v_pk_mul_f32 v[36:37], v[134:135], v[20:21] op_sel_hi:[1,0]
	v_pk_fma_f32 v[24:25], v[178:179], v[18:19], v[16:17] neg_lo:[1,0,0] neg_hi:[1,0,0]
	v_pk_fma_f32 v[146:147], v[178:179], v[36:37], v[42:43] neg_lo:[1,0,0] neg_hi:[1,0,0]
	v_pk_mul_f32 v[36:37], v[132:133], v[20:21] op_sel_hi:[1,0]
	v_pk_mul_f32 v[16:17], v[24:25], v[24:25]
	v_pk_fma_f32 v[152:153], v[178:179], v[36:37], v[40:41] neg_lo:[1,0,0] neg_hi:[1,0,0]
	v_pk_mul_f32 v[36:37], v[138:139], v[20:21] op_sel_hi:[1,0]
	v_pk_fma_f32 v[150:151], v[22:23], v[22:23], v[16:17]
	global_load_dwordx4 v[16:19], v[186:187], off
	global_load_dwordx2 v[78:79], v[188:189], off
	v_pk_fma_f32 v[74:75], v[178:179], v[36:37], v[46:47] neg_lo:[1,0,0] neg_hi:[1,0,0]
	v_pk_mul_f32 v[36:37], v[136:137], v[20:21] op_sel_hi:[1,0]
	v_pk_mul_f32 v[228:229], v[76:77], v[76:77]
	v_pk_fma_f32 v[154:155], v[178:179], v[36:37], v[44:45] neg_lo:[1,0,0] neg_hi:[1,0,0]
	v_pk_mul_f32 v[36:37], v[142:143], v[20:21] op_sel_hi:[1,0]
	v_pk_mul_f32 v[230:231], v[148:149], v[148:149]
	v_pk_fma_f32 v[72:73], v[178:179], v[36:37], v[50:51] neg_lo:[1,0,0] neg_hi:[1,0,0]
	v_pk_mul_f32 v[36:37], v[140:141], v[20:21] op_sel_hi:[1,0]
	v_pk_mul_f32 v[234:235], v[152:153], v[152:153]
	v_pk_fma_f32 v[144:145], v[178:179], v[36:37], v[48:49] neg_lo:[1,0,0] neg_hi:[1,0,0]
	v_pk_mul_f32 v[36:37], v[114:115], v[20:21] op_sel_hi:[1,0]
	v_add_f32_e32 v173, v228, v229
	v_pk_fma_f32 v[68:69], v[178:179], v[36:37], v[54:55] neg_lo:[1,0,0] neg_hi:[1,0,0]
	v_pk_mul_f32 v[36:37], v[112:113], v[20:21] op_sel_hi:[1,0]
	v_pk_mul_f32 v[232:233], v[146:147], v[146:147]
	v_pk_fma_f32 v[70:71], v[178:179], v[36:37], v[52:53] neg_lo:[1,0,0] neg_hi:[1,0,0]
	v_pk_mul_f32 v[36:37], v[118:119], v[20:21] op_sel_hi:[1,0]
	v_pk_mul_f32 v[238:239], v[154:155], v[154:155]
	v_pk_fma_f32 v[64:65], v[178:179], v[36:37], v[58:59] neg_lo:[1,0,0] neg_hi:[1,0,0]
	v_pk_mul_f32 v[36:37], v[116:117], v[20:21] op_sel_hi:[1,0]
	v_pk_mul_f32 v[236:237], v[74:75], v[74:75]
	v_pk_fma_f32 v[66:67], v[178:179], v[36:37], v[56:57] neg_lo:[1,0,0] neg_hi:[1,0,0]
	v_pk_mul_f32 v[36:37], v[122:123], v[20:21] op_sel_hi:[1,0]
	v_pk_mul_f32 v[242:243], v[144:145], v[144:145]
	v_pk_fma_f32 v[60:61], v[178:179], v[36:37], v[60:61] neg_lo:[1,0,0] neg_hi:[1,0,0]
	v_pk_mul_f32 v[36:37], v[120:121], v[20:21] op_sel_hi:[1,0]
	v_pk_mul_f32 v[240:241], v[72:73], v[72:73]
	v_pk_fma_f32 v[62:63], v[178:179], v[36:37], v[62:63] neg_lo:[1,0,0] neg_hi:[1,0,0]
	v_pk_mul_f32 v[36:37], v[126:127], v[20:21] op_sel_hi:[1,0]
	v_pk_mul_f32 v[246:247], v[70:71], v[70:71]
	v_pk_fma_f32 v[56:57], v[178:179], v[36:37], v[158:159] neg_lo:[1,0,0] neg_hi:[1,0,0]
	v_pk_mul_f32 v[36:37], v[124:125], v[20:21] op_sel_hi:[1,0]
	v_pk_mul_f32 v[244:245], v[68:69], v[68:69]
	v_pk_fma_f32 v[58:59], v[178:179], v[36:37], v[156:157] neg_lo:[1,0,0] neg_hi:[1,0,0]
	v_pk_mul_f32 v[36:37], v[98:99], v[20:21] op_sel_hi:[1,0]
	v_pk_mul_f32 v[250:251], v[66:67], v[66:67]
	v_pk_fma_f32 v[52:53], v[178:179], v[36:37], v[162:163] neg_lo:[1,0,0] neg_hi:[1,0,0]
	v_pk_mul_f32 v[36:37], v[96:97], v[20:21] op_sel_hi:[1,0]
	v_pk_mul_f32 v[248:249], v[64:65], v[64:65]
	v_pk_fma_f32 v[54:55], v[178:179], v[36:37], v[160:161] neg_lo:[1,0,0] neg_hi:[1,0,0]
	v_pk_mul_f32 v[36:37], v[102:103], v[20:21] op_sel_hi:[1,0]
	v_pk_mul_f32 v[196:197], v[62:63], v[62:63]
	v_pk_fma_f32 v[48:49], v[178:179], v[36:37], v[166:167] neg_lo:[1,0,0] neg_hi:[1,0,0]
	v_pk_mul_f32 v[36:37], v[100:101], v[20:21] op_sel_hi:[1,0]
	v_pk_mul_f32 v[252:253], v[60:61], v[60:61]
	v_pk_fma_f32 v[50:51], v[178:179], v[36:37], v[164:165] neg_lo:[1,0,0] neg_hi:[1,0,0]
	v_pk_mul_f32 v[36:37], v[106:107], v[20:21] op_sel_hi:[1,0]
	v_pk_mul_f32 v[156:157], v[58:59], v[58:59]
	v_pk_fma_f32 v[44:45], v[178:179], v[36:37], v[170:171] neg_lo:[1,0,0] neg_hi:[1,0,0]
	v_pk_mul_f32 v[36:37], v[104:105], v[20:21] op_sel_hi:[1,0]
	v_pk_mul_f32 v[158:159], v[56:57], v[56:57]
	v_pk_fma_f32 v[46:47], v[178:179], v[36:37], v[168:169] neg_lo:[1,0,0] neg_hi:[1,0,0]
	v_pk_mul_f32 v[36:37], v[110:111], v[20:21] op_sel_hi:[1,0]
	v_add_f32_e32 v156, v156, v157
	v_pk_fma_f32 v[38:39], v[178:179], v[36:37], v[192:193] neg_lo:[1,0,0] neg_hi:[1,0,0]
	v_pk_mul_f32 v[36:37], v[108:109], v[20:21] op_sel_hi:[1,0]
	v_pk_mul_f32 v[160:161], v[54:55], v[54:55]
	v_pk_fma_f32 v[42:43], v[178:179], v[36:37], v[30:31] neg_lo:[1,0,0] neg_hi:[1,0,0]
	v_mov_b32_e32 v37, v39
	v_mov_b32_e32 v36, v43
	v_mov_b32_e32 v30, v42
	v_mov_b32_e32 v31, v38
	v_pk_mul_f32 v[36:37], v[36:37], v[36:37]
	v_pk_mul_f32 v[162:163], v[52:53], v[52:53]
	v_pk_fma_f32 v[192:193], v[30:31], v[30:31], v[36:37]
	v_pk_mul_f32 v[30:31], v[82:83], v[20:21] op_sel_hi:[1,0]
	v_pk_mul_f32 v[164:165], v[50:51], v[50:51]
	v_pk_fma_f32 v[36:37], v[178:179], v[30:31], v[224:225] neg_lo:[1,0,0] neg_hi:[1,0,0]
	v_pk_mul_f32 v[30:31], v[80:81], v[20:21] op_sel_hi:[1,0]
	v_pk_mul_f32 v[224:225], v[84:85], v[20:21] op_sel_hi:[1,0]
	v_pk_fma_f32 v[40:41], v[178:179], v[30:31], v[222:223] neg_lo:[1,0,0] neg_hi:[1,0,0]
	v_mov_b32_e32 v223, v37
	v_mov_b32_e32 v222, v41
	v_mov_b32_e32 v30, v40
	v_mov_b32_e32 v31, v36
	v_pk_mul_f32 v[222:223], v[222:223], v[222:223]
	v_pk_fma_f32 v[34:35], v[178:179], v[224:225], v[34:35] neg_lo:[1,0,0] neg_hi:[1,0,0]
	v_pk_fma_f32 v[222:223], v[30:31], v[30:31], v[222:223]
	v_pk_mul_f32 v[30:31], v[86:87], v[20:21] op_sel_hi:[1,0]
	v_mov_b32_e32 v224, v34
	v_pk_fma_f32 v[30:31], v[178:179], v[30:31], v[226:227] neg_lo:[1,0,0] neg_hi:[1,0,0]
	v_mov_b32_e32 v226, v35
	v_mov_b32_e32 v227, v31
	v_mov_b32_e32 v225, v30
	v_pk_mul_f32 v[226:227], v[226:227], v[226:227]
	v_add_f32_e32 v21, v234, v235
	v_pk_fma_f32 v[224:225], v[224:225], v[224:225], v[226:227]
	v_add_f32_e32 v226, v230, v231
	v_add_f32_e32 v173, v226, v173
	v_add_f32_e32 v21, v173, v21
	v_add_f32_e32 v173, v232, v233
	v_add_f32_e32 v21, v21, v173
	v_add_f32_e32 v173, v238, v239
	v_add_f32_e32 v21, v21, v173
	v_add_f32_e32 v173, v236, v237
	v_add_f32_e32 v21, v21, v173
	v_add_f32_e32 v173, v242, v243
	v_add_f32_e32 v21, v21, v173
	v_add_f32_e32 v173, v240, v241
	v_add_f32_e32 v21, v21, v173
	v_add_f32_e32 v173, v246, v247
	v_add_f32_e32 v21, v21, v173
	v_add_f32_e32 v173, v244, v245
	v_add_f32_e32 v21, v21, v173
	v_add_f32_e32 v173, v250, v251
	v_add_f32_e32 v21, v21, v173
	v_add_f32_e32 v173, v248, v249
	v_add_f32_e32 v21, v21, v173
	v_add_f32_e32 v173, v196, v197
	v_add_f32_e32 v21, v21, v173
	v_add_f32_e32 v173, v252, v253
	v_add_f32_e32 v21, v21, v173
	v_add_f32_e32 v21, v21, v156
	v_add_f32_e32 v156, v158, v159
	v_add_f32_e32 v21, v21, v156
	v_add_f32_e32 v156, v160, v161
	v_add_f32_e32 v21, v21, v156
	v_add_f32_e32 v156, v162, v163
	v_pk_mul_f32 v[166:167], v[48:49], v[48:49]
	v_add_f32_e32 v21, v21, v156
	v_add_f32_e32 v156, v164, v165
	v_pk_mul_f32 v[168:169], v[46:47], v[46:47]
	v_add_f32_e32 v21, v21, v156
	v_add_f32_e32 v156, v166, v167
	v_pk_mul_f32 v[170:171], v[44:45], v[44:45]
	v_add_f32_e32 v21, v21, v156
	v_add_f32_e32 v156, v168, v169
	v_add_f32_e32 v21, v21, v156
	v_add_f32_e32 v156, v170, v171
	v_add_f32_e32 v21, v21, v156
	v_add_f32_e32 v21, v21, v192
	v_add_f32_e32 v21, v21, v193
	v_add_f32_e32 v21, v21, v222
	v_add_f32_e32 v21, v21, v223
	v_add_f32_e32 v21, v21, v224
	v_add_f32_e32 v21, v21, v225
	v_add_f32_e32 v21, v21, v32
	v_add_f32_e32 v21, v21, v33
	v_add_f32_e32 v21, v21, v150
	v_add_f32_e32 v21, v21, v151
	ds_bpermute_b32 v32, v221, v21
	global_load_dwordx2 v[80:81], v[188:189], off offset:16
	global_load_dwordx4 v[112:115], v[186:187], off offset:32
	global_load_dwordx4 v[116:119], v[186:187], off offset:64
	global_load_dwordx2 v[82:83], v[188:189], off offset:32
	global_load_dwordx2 v[84:85], v[188:189], off offset:48
	global_load_dwordx4 v[120:123], v[186:187], off offset:96
	global_load_dwordx4 v[124:127], v[186:187], off offset:128
	global_load_dwordx2 v[86:87], v[188:189], off offset:64
	global_load_dwordx2 v[88:89], v[188:189], off offset:80
	global_load_dwordx4 v[128:131], v[186:187], off offset:160
	global_load_dwordx4 v[132:135], v[186:187], off offset:192
	global_load_dwordx2 v[90:91], v[188:189], off offset:96
	global_load_dwordx2 v[92:93], v[188:189], off offset:112
	global_load_dwordx4 v[136:139], v[186:187], off offset:224
	global_load_dwordx4 v[140:143], v[186:187], off offset:256
	global_load_dwordx2 v[94:95], v[188:189], off offset:128
	global_load_dwordx2 v[96:97], v[188:189], off offset:144
	global_load_dwordx4 v[158:161], v[186:187], off offset:288
	global_load_dwordx4 v[162:165], v[186:187], off offset:320
	global_load_dwordx2 v[98:99], v[188:189], off offset:160
	global_load_dwordx2 v[100:101], v[188:189], off offset:176
	global_load_dwordx4 v[166:169], v[186:187], off offset:352
	global_load_dwordx4 v[108:111], v[186:187], off offset:384
	global_load_dwordx2 v[102:103], v[188:189], off offset:192
	global_load_dwordx2 v[104:105], v[188:189], off offset:208
	global_load_dwordx2 v[106:107], v[188:189], off offset:224
	global_load_dwordx2 v[170:171], v[188:189], off offset:240
	global_load_dwordx4 v[222:225], v[186:187], off offset:416
	global_load_dwordx4 v[226:229], v[186:187], off offset:448
	global_load_dwordx4 v[230:233], v[186:187], off offset:480
	v_mbcnt_lo_u32_b32 v250, -1, 0
	v_mbcnt_hi_u32_b32 v250, -1, v250
	v_and_b32_e32 v250, 32, v250
	v_lshrrev_b32_e32 v250, 2, v250
	v_mov_b32_e32 v251, 0
	v_lshl_add_u64 v[252:253], v[190:191], 0, v[250:251]
	s_waitcnt vmcnt(30)
	v_lshlrev_b32_e32 v156, 16, v78
	v_and_b32_e32 v157, 0xffff0000, v78
	v_lshlrev_b32_e32 v78, 16, v79
	v_and_b32_e32 v79, 0xffff0000, v79
	s_waitcnt lgkmcnt(0)
	v_add_f32_e32 v21, v21, v32
	v_fmamk_f32 v21, v21, 0x3c000000, v195
	v_mul_f32_e32 v32, 0x4b800000, v21
	v_cmp_gt_f32_e32 vcc, s15, v21
	s_nop 0
	v_cndmask_b32_e32 v21, v21, v32, vcc
	v_rsq_f32_e32 v21, v21
	s_nop 0
	v_mul_f32_e32 v32, 0x45800000, v21
	v_cndmask_b32_e32 v21, v21, v32, vcc
	v_mul_f32_e32 v32, v207, v21
	v_pk_mul_f32 v[148:149], v[148:149], v[32:33] op_sel_hi:[1,0]
	v_pk_mul_f32 v[76:77], v[76:77], v[32:33] op_sel_hi:[1,0]
	v_pk_mul_f32 v[16:17], v[16:17], v[148:149]
	v_pk_mul_f32 v[18:19], v[18:19], v[76:77]
	v_pk_mul_f32 v[16:17], v[16:17], v[156:157]
	v_pk_mul_f32 v[18:19], v[18:19], v[78:79]
	v_cvt_pk_bf16_f32 v236, v16, v17
	v_cvt_pk_bf16_f32 v237, v18, v19
	v_pk_mul_f32 v[148:149], v[152:153], v[32:33] op_sel_hi:[1,0]
	v_pk_mul_f32 v[74:75], v[74:75], v[32:33] op_sel_hi:[1,0]
	v_pk_mul_f32 v[72:73], v[72:73], v[32:33] op_sel_hi:[1,0]
	v_pk_mul_f32 v[70:71], v[70:71], v[32:33] op_sel_hi:[1,0]
	v_pk_mul_f32 v[68:69], v[68:69], v[32:33] op_sel_hi:[1,0]
	v_pk_mul_f32 v[66:67], v[66:67], v[32:33] op_sel_hi:[1,0]
	v_pk_mul_f32 v[64:65], v[64:65], v[32:33] op_sel_hi:[1,0]
	v_pk_mul_f32 v[62:63], v[62:63], v[32:33] op_sel_hi:[1,0]
	v_pk_mul_f32 v[60:61], v[60:61], v[32:33] op_sel_hi:[1,0]
	v_pk_mul_f32 v[58:59], v[58:59], v[32:33] op_sel_hi:[1,0]
	v_pk_mul_f32 v[56:57], v[56:57], v[32:33] op_sel_hi:[1,0]
	v_pk_mul_f32 v[54:55], v[54:55], v[32:33] op_sel_hi:[1,0]
	v_pk_mul_f32 v[52:53], v[52:53], v[32:33] op_sel_hi:[1,0]
	v_pk_mul_f32 v[50:51], v[50:51], v[32:33] op_sel_hi:[1,0]
	v_pk_mul_f32 v[48:49], v[48:49], v[32:33] op_sel_hi:[1,0]
	v_pk_mul_f32 v[46:47], v[46:47], v[32:33] op_sel_hi:[1,0]
	v_pk_mul_f32 v[44:45], v[44:45], v[32:33] op_sel_hi:[1,0]
	v_pk_mul_f32 v[42:43], v[42:43], v[32:33] op_sel_hi:[1,0]
	v_pk_mul_f32 v[38:39], v[38:39], v[32:33] op_sel_hi:[1,0]
	v_pk_mul_f32 v[40:41], v[40:41], v[32:33] op_sel_hi:[1,0]
	v_pk_mul_f32 v[36:37], v[36:37], v[32:33] op_sel_hi:[1,0]
	v_pk_mul_f32 v[34:35], v[34:35], v[32:33] op_sel_hi:[1,0]
	v_pk_mul_f32 v[30:31], v[30:31], v[32:33] op_sel_hi:[1,0]
	s_waitcnt vmcnt(29)
	v_lshlrev_b32_e32 v76, 16, v80
	v_and_b32_e32 v77, 0xffff0000, v80
	v_lshlrev_b32_e32 v78, 16, v81
	v_and_b32_e32 v79, 0xffff0000, v81
	s_waitcnt vmcnt(28)
	v_pk_mul_f32 v[16:17], v[112:113], v[148:149]
	s_nop 0
	v_pk_mul_f32 v[16:17], v[16:17], v[76:77]
	v_pk_mul_f32 v[76:77], v[146:147], v[32:33] op_sel_hi:[1,0]
	v_cvt_pk_bf16_f32 v238, v16, v17
	v_pk_mul_f32 v[18:19], v[114:115], v[76:77]
	s_nop 0
	v_pk_mul_f32 v[18:19], v[18:19], v[78:79]
	v_pk_mul_f32 v[78:79], v[154:155], v[32:33] op_sel_hi:[1,0]
	v_cvt_pk_bf16_f32 v239, v18, v19
	s_nop 1
	v_permlane32_swap_b32 v236, v238
	v_permlane32_swap_b32 v237, v239
	global_store_dwordx4 v[252:253], v[236:239], off
	s_waitcnt vmcnt(28)
	v_pk_mul_f32 v[16:17], v[116:117], v[78:79]
	s_waitcnt vmcnt(27)
	v_lshlrev_b32_e32 v146, 16, v82
	v_and_b32_e32 v147, 0xffff0000, v82
	v_pk_mul_f32 v[18:19], v[118:119], v[74:75]
	v_lshlrev_b32_e32 v74, 16, v83
	v_and_b32_e32 v75, 0xffff0000, v83
	v_pk_mul_f32 v[16:17], v[16:17], v[146:147]
	v_pk_mul_f32 v[18:19], v[18:19], v[74:75]
	v_cvt_pk_bf16_f32 v236, v16, v17
	v_cvt_pk_bf16_f32 v237, v18, v19
	v_pk_mul_f32 v[74:75], v[144:145], v[32:33] op_sel_hi:[1,0]
	s_waitcnt vmcnt(26)
	v_lshlrev_b32_e32 v76, 16, v84
	v_and_b32_e32 v77, 0xffff0000, v84
	v_lshlrev_b32_e32 v78, 16, v85
	v_and_b32_e32 v79, 0xffff0000, v85
	s_waitcnt vmcnt(25)
	v_pk_mul_f32 v[16:17], v[120:121], v[74:75]
	v_pk_mul_f32 v[18:19], v[122:123], v[72:73]
	v_pk_mul_f32 v[16:17], v[16:17], v[76:77]
	v_pk_mul_f32 v[18:19], v[18:19], v[78:79]
	v_cvt_pk_bf16_f32 v238, v16, v17
	v_cvt_pk_bf16_f32 v239, v18, v19
	s_nop 1
	v_permlane32_swap_b32 v236, v238
	v_permlane32_swap_b32 v237, v239
	global_store_dwordx4 v[252:253], v[236:239], off offset:32
	s_waitcnt vmcnt(25)
	v_pk_mul_f32 v[16:17], v[70:71], v[124:125]
	s_waitcnt vmcnt(24)
	v_lshlrev_b32_e32 v70, 16, v86
	v_and_b32_e32 v71, 0xffff0000, v86
	v_pk_mul_f32 v[18:19], v[68:69], v[126:127]
	v_lshlrev_b32_e32 v68, 16, v87
	v_and_b32_e32 v69, 0xffff0000, v87
	v_pk_mul_f32 v[16:17], v[16:17], v[70:71]
	v_pk_mul_f32 v[18:19], v[18:19], v[68:69]
	v_cvt_pk_bf16_f32 v236, v16, v17
	v_cvt_pk_bf16_f32 v237, v18, v19
	s_waitcnt vmcnt(23)
	v_lshlrev_b32_e32 v68, 16, v88
	v_and_b32_e32 v69, 0xffff0000, v88
	v_lshlrev_b32_e32 v70, 16, v89
	v_and_b32_e32 v71, 0xffff0000, v89
	s_waitcnt vmcnt(22)
	v_pk_mul_f32 v[16:17], v[66:67], v[128:129]
	v_pk_mul_f32 v[18:19], v[64:65], v[130:131]
	v_pk_mul_f32 v[16:17], v[16:17], v[68:69]
	v_pk_mul_f32 v[18:19], v[18:19], v[70:71]
	v_cvt_pk_bf16_f32 v238, v16, v17
	v_cvt_pk_bf16_f32 v239, v18, v19
	s_nop 1
	v_permlane32_swap_b32 v236, v238
	v_permlane32_swap_b32 v237, v239
	global_store_dwordx4 v[252:253], v[236:239], off offset:64
	s_waitcnt vmcnt(22)
	v_pk_mul_f32 v[16:17], v[62:63], v[132:133]
	s_waitcnt vmcnt(21)
	v_lshlrev_b32_e32 v62, 16, v90
	v_and_b32_e32 v63, 0xffff0000, v90
	v_pk_mul_f32 v[18:19], v[60:61], v[134:135]
	v_lshlrev_b32_e32 v60, 16, v91
	v_and_b32_e32 v61, 0xffff0000, v91
	v_pk_mul_f32 v[16:17], v[16:17], v[62:63]
	v_pk_mul_f32 v[18:19], v[18:19], v[60:61]
	v_cvt_pk_bf16_f32 v236, v16, v17
	v_cvt_pk_bf16_f32 v237, v18, v19
	s_waitcnt vmcnt(20)
	v_lshlrev_b32_e32 v60, 16, v92
	v_and_b32_e32 v61, 0xffff0000, v92
	v_lshlrev_b32_e32 v62, 16, v93
	v_and_b32_e32 v63, 0xffff0000, v93
	s_waitcnt vmcnt(19)
	v_pk_mul_f32 v[16:17], v[58:59], v[136:137]
	v_pk_mul_f32 v[18:19], v[56:57], v[138:139]
	v_pk_mul_f32 v[16:17], v[16:17], v[60:61]
	v_pk_mul_f32 v[18:19], v[18:19], v[62:63]
	v_cvt_pk_bf16_f32 v238, v16, v17
	v_cvt_pk_bf16_f32 v239, v18, v19
	s_nop 1
	v_permlane32_swap_b32 v236, v238
	v_permlane32_swap_b32 v237, v239
	global_store_dwordx4 v[252:253], v[236:239], off offset:96
	s_waitcnt vmcnt(19)
	v_pk_mul_f32 v[16:17], v[54:55], v[140:141]
	s_waitcnt vmcnt(18)
	v_lshlrev_b32_e32 v54, 16, v94
	v_and_b32_e32 v55, 0xffff0000, v94
	v_pk_mul_f32 v[18:19], v[52:53], v[142:143]
	v_lshlrev_b32_e32 v52, 16, v95
	v_and_b32_e32 v53, 0xffff0000, v95
	v_pk_mul_f32 v[16:17], v[16:17], v[54:55]
	v_pk_mul_f32 v[18:19], v[18:19], v[52:53]
	v_cvt_pk_bf16_f32 v236, v16, v17
	v_cvt_pk_bf16_f32 v237, v18, v19
	s_waitcnt vmcnt(17)
	v_lshlrev_b32_e32 v52, 16, v96
	v_and_b32_e32 v53, 0xffff0000, v96
	v_lshlrev_b32_e32 v54, 16, v97
	v_and_b32_e32 v55, 0xffff0000, v97
	s_waitcnt vmcnt(16)
	v_pk_mul_f32 v[16:17], v[50:51], v[158:159]
	v_pk_mul_f32 v[18:19], v[48:49], v[160:161]
	v_pk_mul_f32 v[16:17], v[16:17], v[52:53]
	v_pk_mul_f32 v[18:19], v[18:19], v[54:55]
	v_cvt_pk_bf16_f32 v238, v16, v17
	v_cvt_pk_bf16_f32 v239, v18, v19
	s_nop 1
	v_permlane32_swap_b32 v236, v238
	v_permlane32_swap_b32 v237, v239
	global_store_dwordx4 v[252:253], v[236:239], off offset:128
	s_waitcnt vmcnt(16)
	v_pk_mul_f32 v[16:17], v[46:47], v[162:163]
	s_waitcnt vmcnt(15)
	v_lshlrev_b32_e32 v46, 16, v98
	v_and_b32_e32 v47, 0xffff0000, v98
	v_pk_mul_f32 v[18:19], v[44:45], v[164:165]
	v_lshlrev_b32_e32 v44, 16, v99
	v_and_b32_e32 v45, 0xffff0000, v99
	v_pk_mul_f32 v[16:17], v[16:17], v[46:47]
	v_pk_mul_f32 v[18:19], v[18:19], v[44:45]
	v_cvt_pk_bf16_f32 v236, v16, v17
	v_cvt_pk_bf16_f32 v237, v18, v19
	s_waitcnt vmcnt(14)
	v_lshlrev_b32_e32 v44, 16, v100
	v_and_b32_e32 v45, 0xffff0000, v100
	v_lshlrev_b32_e32 v46, 16, v101
	v_and_b32_e32 v47, 0xffff0000, v101
	s_waitcnt vmcnt(13)
	v_pk_mul_f32 v[16:17], v[42:43], v[166:167]
	v_pk_mul_f32 v[18:19], v[38:39], v[168:169]
	v_pk_mul_f32 v[16:17], v[16:17], v[44:45]
	v_pk_mul_f32 v[18:19], v[18:19], v[46:47]
	v_cvt_pk_bf16_f32 v238, v16, v17
	v_cvt_pk_bf16_f32 v239, v18, v19
	s_nop 1
	v_permlane32_swap_b32 v236, v238
	v_permlane32_swap_b32 v237, v239
	global_store_dwordx4 v[252:253], v[236:239], off offset:160
	s_waitcnt vmcnt(13)
	v_pk_mul_f32 v[16:17], v[40:41], v[108:109]
	s_waitcnt vmcnt(12)
	v_lshlrev_b32_e32 v40, 16, v102
	v_and_b32_e32 v41, 0xffff0000, v102
	v_pk_mul_f32 v[18:19], v[36:37], v[110:111]
	v_lshlrev_b32_e32 v36, 16, v103
	v_and_b32_e32 v37, 0xffff0000, v103
	v_pk_mul_f32 v[16:17], v[16:17], v[40:41]
	v_pk_mul_f32 v[18:19], v[18:19], v[36:37]
	v_cvt_pk_bf16_f32 v236, v16, v17
	v_cvt_pk_bf16_f32 v237, v18, v19
	s_waitcnt vmcnt(11)
	v_lshlrev_b32_e32 v36, 16, v104
	v_and_b32_e32 v37, 0xffff0000, v104
	v_lshlrev_b32_e32 v38, 16, v105
	v_and_b32_e32 v39, 0xffff0000, v105
	s_waitcnt vmcnt(8)
	v_pk_mul_f32 v[16:17], v[34:35], v[222:223]
	v_pk_mul_f32 v[18:19], v[30:31], v[224:225]
	v_pk_mul_f32 v[16:17], v[16:17], v[36:37]
	v_pk_mul_f32 v[18:19], v[18:19], v[38:39]
	v_cvt_pk_bf16_f32 v238, v16, v17
	v_cvt_pk_bf16_f32 v239, v18, v19
	s_nop 1
	v_permlane32_swap_b32 v236, v238
	v_permlane32_swap_b32 v237, v239
	global_store_dwordx4 v[252:253], v[236:239], off offset:192
	v_mov_b32_e32 v34, v26
	v_mov_b32_e32 v35, v28
	v_mov_b32_e32 v28, v27
	v_pk_mul_f32 v[26:27], v[34:35], v[32:33] op_sel_hi:[1,0]
	v_pk_mul_f32 v[28:29], v[28:29], v[32:33] op_sel_hi:[1,0]
	s_waitcnt vmcnt(8)
	v_pk_mul_f32 v[16:17], v[26:27], v[226:227]
	v_lshlrev_b32_e32 v26, 16, v106
	v_and_b32_e32 v27, 0xffff0000, v106
	v_pk_mul_f32 v[18:19], v[28:29], v[228:229]
	v_lshlrev_b32_e32 v28, 16, v107
	v_and_b32_e32 v29, 0xffff0000, v107
	v_pk_mul_f32 v[16:17], v[16:17], v[26:27]
	v_pk_mul_f32 v[18:19], v[18:19], v[28:29]
	v_cvt_pk_bf16_f32 v236, v16, v17
	v_cvt_pk_bf16_f32 v237, v18, v19
	v_mov_b32_e32 v26, v22
	v_mov_b32_e32 v27, v24
	v_mov_b32_e32 v24, v23
	v_pk_mul_f32 v[22:23], v[26:27], v[32:33] op_sel_hi:[1,0]
	v_pk_mul_f32 v[24:25], v[24:25], v[32:33] op_sel_hi:[1,0]
	v_lshlrev_b32_e32 v26, 16, v170
	v_and_b32_e32 v27, 0xffff0000, v170
	v_lshlrev_b32_e32 v28, 16, v171
	v_and_b32_e32 v29, 0xffff0000, v171
	s_waitcnt vmcnt(7)
	v_pk_mul_f32 v[16:17], v[22:23], v[230:231]
	v_pk_mul_f32 v[18:19], v[24:25], v[232:233]
	v_pk_mul_f32 v[16:17], v[16:17], v[26:27]
	v_pk_mul_f32 v[18:19], v[18:19], v[28:29]
	v_cvt_pk_bf16_f32 v238, v16, v17
	v_cvt_pk_bf16_f32 v239, v18, v19
	s_nop 1
	v_permlane32_swap_b32 v236, v238
	v_permlane32_swap_b32 v237, v239
	global_store_dwordx4 v[252:253], v[236:239], off offset:224
	s_cbranch_execnz .LBB0_498
	s_branch .LBB0_530

.LBB0_562:
	ds_bpermute_b32 v16, v221, v193
	s_waitcnt lgkmcnt(0)
	s_barrier
	s_waitcnt lgkmcnt(0)
	v_add_f32_e32 v16, v193, v16
	v_div_scale_f32 v17, s[16:17], v16, v16, 1.0
	v_rcp_f32_e32 v18, v17
	v_div_scale_f32 v19, vcc, 1.0, v16, 1.0
	v_fma_f32 v20, -v17, v18, 1.0
	v_fmac_f32_e32 v18, v20, v18
	v_mul_f32_e32 v20, v19, v18
	v_fma_f32 v21, -v17, v20, v19
	v_fmac_f32_e32 v20, v21, v18
	v_fma_f32 v17, -v17, v20, v19
	v_div_fmas_f32 v17, v17, v18, v20
	v_div_fixup_f32 v20, v17, v16, 1.0
	v_cndmask_b32_e64 v16, 0, 1, s[6:7]
	v_cmp_ne_u32_e64 s[72:73], 1, v16
	s_andn2_b64 vcc, exec, s[6:7]
	s_mov_b64 s[6:7], -1
	s_cbranch_vccnz .LBB0_564
	ds_read2st64_b32 v[16:17], v209 offset0:224 offset1:225
	ds_read2st64_b32 v[18:19], v209 offset0:226 offset1:227
	ds_read2st64_b32 v[22:23], v209 offset0:228 offset1:229
	ds_read2st64_b32 v[24:25], v209 offset0:230 offset1:231
	v_pk_mul_f32 v[64:65], v[130:131], v[20:21] op_sel_hi:[1,0]
	s_waitcnt lgkmcnt(3)
	v_lshlrev_b32_e32 v36, 16, v16
	v_and_b32_e32 v37, 0xffff0000, v16
	v_lshlrev_b32_e32 v38, 16, v17
	v_and_b32_e32 v39, 0xffff0000, v17
	ds_read2st64_b32 v[16:17], v209 offset0:232 offset1:233
	s_waitcnt lgkmcnt(3)
	v_lshlrev_b32_e32 v40, 16, v18
	v_and_b32_e32 v41, 0xffff0000, v18
	v_lshlrev_b32_e32 v42, 16, v19
	v_and_b32_e32 v43, 0xffff0000, v19
	s_waitcnt lgkmcnt(2)
	v_lshlrev_b32_e32 v44, 16, v22
	v_and_b32_e32 v45, 0xffff0000, v22
	v_lshlrev_b32_e32 v46, 16, v23
	v_and_b32_e32 v47, 0xffff0000, v23
	s_waitcnt lgkmcnt(1)
	v_lshlrev_b32_e32 v48, 16, v24
	v_and_b32_e32 v49, 0xffff0000, v24
	v_lshlrev_b32_e32 v50, 16, v25
	v_and_b32_e32 v51, 0xffff0000, v25
	ds_read2st64_b32 v[18:19], v209 offset0:234 offset1:235
	ds_read2st64_b32 v[22:23], v209 offset0:236 offset1:237
	ds_read2st64_b32 v[24:25], v209 offset0:238 offset1:239
	s_waitcnt lgkmcnt(3)
	v_lshlrev_b32_e32 v52, 16, v16
	v_and_b32_e32 v53, 0xffff0000, v16
	v_lshlrev_b32_e32 v54, 16, v17
	v_and_b32_e32 v55, 0xffff0000, v17
	ds_read2st64_b32 v[16:17], v209 offset0:240 offset1:241
	s_waitcnt lgkmcnt(3)
	v_lshlrev_b32_e32 v56, 16, v18
	v_and_b32_e32 v57, 0xffff0000, v18
	v_lshlrev_b32_e32 v58, 16, v19
	v_and_b32_e32 v59, 0xffff0000, v19
	s_waitcnt lgkmcnt(2)
	v_lshlrev_b32_e32 v62, 16, v22
	v_and_b32_e32 v63, 0xffff0000, v22
	v_lshlrev_b32_e32 v60, 16, v23
	v_and_b32_e32 v61, 0xffff0000, v23
	s_waitcnt lgkmcnt(1)
	v_lshlrev_b32_e32 v156, 16, v24
	v_and_b32_e32 v157, 0xffff0000, v24
	v_lshlrev_b32_e32 v158, 16, v25
	v_and_b32_e32 v159, 0xffff0000, v25
	ds_read2st64_b32 v[18:19], v209 offset0:242 offset1:243
	ds_read2st64_b32 v[22:23], v209 offset0:244 offset1:245
	ds_read2st64_b32 v[24:25], v209 offset0:246 offset1:247
	s_waitcnt lgkmcnt(3)
	v_lshlrev_b32_e32 v160, 16, v16
	v_and_b32_e32 v161, 0xffff0000, v16
	v_lshlrev_b32_e32 v162, 16, v17
	v_and_b32_e32 v163, 0xffff0000, v17
	ds_read2st64_b32 v[16:17], v209 offset0:248 offset1:249
	s_waitcnt lgkmcnt(3)
	v_lshlrev_b32_e32 v164, 16, v18
	v_and_b32_e32 v165, 0xffff0000, v18
	v_lshlrev_b32_e32 v166, 16, v19
	v_and_b32_e32 v167, 0xffff0000, v19
	s_waitcnt lgkmcnt(2)
	v_lshlrev_b32_e32 v168, 16, v22
	v_and_b32_e32 v169, 0xffff0000, v22
	v_lshlrev_b32_e32 v170, 16, v23
	v_and_b32_e32 v171, 0xffff0000, v23
	s_waitcnt lgkmcnt(1)
	v_lshlrev_b32_e32 v30, 16, v24
	v_and_b32_e32 v31, 0xffff0000, v24
	v_lshlrev_b32_e32 v192, 16, v25
	v_and_b32_e32 v193, 0xffff0000, v25
	ds_read2st64_b32 v[18:19], v209 offset0:250 offset1:251
	ds_read2st64_b32 v[22:23], v209 offset0:252 offset1:253
	ds_read2st64_b32 v[24:25], v209 offset0:254 offset1:255
	s_waitcnt lgkmcnt(3)
	v_lshlrev_b32_e32 v196, 16, v16
	v_and_b32_e32 v197, 0xffff0000, v16
	s_waitcnt lgkmcnt(2)
	v_lshlrev_b32_e32 v34, 16, v18
	v_and_b32_e32 v35, 0xffff0000, v18
	v_lshlrev_b32_e32 v224, 16, v19
	v_and_b32_e32 v225, 0xffff0000, v19
	v_mov_b32_e32 v18, v88
	v_mov_b32_e32 v19, v90
	v_lshlrev_b32_e32 v222, 16, v17
	v_and_b32_e32 v223, 0xffff0000, v17
	s_waitcnt lgkmcnt(1)
	v_lshlrev_b32_e32 v17, 16, v23
	v_lshlrev_b32_e32 v16, 16, v22
	v_pk_mul_f32 v[18:19], v[18:19], v[20:21] op_sel_hi:[1,0]
	v_pk_fma_f32 v[76:77], v[178:179], v[64:65], v[38:39] neg_lo:[1,0,0] neg_hi:[1,0,0]
	v_pk_fma_f32 v[26:27], v[178:179], v[18:19], v[16:17] neg_lo:[1,0,0] neg_hi:[1,0,0]
	v_mov_b32_e32 v18, v89
	v_mov_b32_e32 v19, v91
	v_and_b32_e32 v17, 0xffff0000, v23
	v_and_b32_e32 v16, 0xffff0000, v22
	v_pk_mul_f32 v[18:19], v[18:19], v[20:21] op_sel_hi:[1,0]
	v_pk_mul_f32 v[38:39], v[128:129], v[20:21] op_sel_hi:[1,0]
	v_pk_fma_f32 v[28:29], v[178:179], v[18:19], v[16:17] neg_lo:[1,0,0] neg_hi:[1,0,0]
	v_mov_b32_e32 v18, v92
	v_pk_mul_f32 v[16:17], v[28:29], v[28:29]
	v_mov_b32_e32 v19, v94
	v_pk_fma_f32 v[32:33], v[26:27], v[26:27], v[16:17]
	s_waitcnt lgkmcnt(0)
	v_lshlrev_b32_e32 v17, 16, v25
	v_lshlrev_b32_e32 v16, 16, v24
	v_pk_mul_f32 v[18:19], v[18:19], v[20:21] op_sel_hi:[1,0]
	v_pk_fma_f32 v[148:149], v[178:179], v[38:39], v[36:37] neg_lo:[1,0,0] neg_hi:[1,0,0]
	v_pk_fma_f32 v[22:23], v[178:179], v[18:19], v[16:17] neg_lo:[1,0,0] neg_hi:[1,0,0]
	v_mov_b32_e32 v18, v93
	v_mov_b32_e32 v19, v95
	v_and_b32_e32 v17, 0xffff0000, v25
	v_and_b32_e32 v16, 0xffff0000, v24
	v_pk_mul_f32 v[18:19], v[18:19], v[20:21] op_sel_hi:[1,0]
	v_pk_mul_f32 v[36:37], v[134:135], v[20:21] op_sel_hi:[1,0]
	v_pk_fma_f32 v[24:25], v[178:179], v[18:19], v[16:17] neg_lo:[1,0,0] neg_hi:[1,0,0]
	v_pk_fma_f32 v[146:147], v[178:179], v[36:37], v[42:43] neg_lo:[1,0,0] neg_hi:[1,0,0]
	v_pk_mul_f32 v[36:37], v[132:133], v[20:21] op_sel_hi:[1,0]
	v_pk_mul_f32 v[16:17], v[24:25], v[24:25]
	v_pk_fma_f32 v[152:153], v[178:179], v[36:37], v[40:41] neg_lo:[1,0,0] neg_hi:[1,0,0]
	v_pk_mul_f32 v[36:37], v[138:139], v[20:21] op_sel_hi:[1,0]
	v_pk_fma_f32 v[150:151], v[22:23], v[22:23], v[16:17]
	global_load_dwordx4 v[16:19], v[186:187], off
	global_load_dwordx2 v[78:79], v[188:189], off
	v_pk_fma_f32 v[74:75], v[178:179], v[36:37], v[46:47] neg_lo:[1,0,0] neg_hi:[1,0,0]
	v_pk_mul_f32 v[36:37], v[136:137], v[20:21] op_sel_hi:[1,0]
	v_pk_mul_f32 v[226:227], v[76:77], v[76:77]
	v_pk_fma_f32 v[154:155], v[178:179], v[36:37], v[44:45] neg_lo:[1,0,0] neg_hi:[1,0,0]
	v_pk_mul_f32 v[36:37], v[142:143], v[20:21] op_sel_hi:[1,0]
	v_pk_mul_f32 v[228:229], v[148:149], v[148:149]
	v_pk_fma_f32 v[72:73], v[178:179], v[36:37], v[50:51] neg_lo:[1,0,0] neg_hi:[1,0,0]
	v_pk_mul_f32 v[36:37], v[140:141], v[20:21] op_sel_hi:[1,0]
	v_pk_mul_f32 v[232:233], v[152:153], v[152:153]
	v_pk_fma_f32 v[144:145], v[178:179], v[36:37], v[48:49] neg_lo:[1,0,0] neg_hi:[1,0,0]
	v_pk_mul_f32 v[36:37], v[114:115], v[20:21] op_sel_hi:[1,0]
	v_add_f32_e32 v173, v226, v227
	v_pk_fma_f32 v[68:69], v[178:179], v[36:37], v[54:55] neg_lo:[1,0,0] neg_hi:[1,0,0]
	v_pk_mul_f32 v[36:37], v[112:113], v[20:21] op_sel_hi:[1,0]
	v_pk_mul_f32 v[230:231], v[146:147], v[146:147]
	v_pk_fma_f32 v[70:71], v[178:179], v[36:37], v[52:53] neg_lo:[1,0,0] neg_hi:[1,0,0]
	v_pk_mul_f32 v[36:37], v[118:119], v[20:21] op_sel_hi:[1,0]
	v_pk_mul_f32 v[236:237], v[154:155], v[154:155]
	v_pk_fma_f32 v[64:65], v[178:179], v[36:37], v[58:59] neg_lo:[1,0,0] neg_hi:[1,0,0]
	v_pk_mul_f32 v[36:37], v[116:117], v[20:21] op_sel_hi:[1,0]
	v_pk_mul_f32 v[234:235], v[74:75], v[74:75]
	v_pk_fma_f32 v[66:67], v[178:179], v[36:37], v[56:57] neg_lo:[1,0,0] neg_hi:[1,0,0]
	v_pk_mul_f32 v[36:37], v[122:123], v[20:21] op_sel_hi:[1,0]
	v_pk_mul_f32 v[240:241], v[144:145], v[144:145]
	v_pk_fma_f32 v[60:61], v[178:179], v[36:37], v[60:61] neg_lo:[1,0,0] neg_hi:[1,0,0]
	v_pk_mul_f32 v[36:37], v[120:121], v[20:21] op_sel_hi:[1,0]
	v_pk_mul_f32 v[238:239], v[72:73], v[72:73]
	v_pk_fma_f32 v[62:63], v[178:179], v[36:37], v[62:63] neg_lo:[1,0,0] neg_hi:[1,0,0]
	v_pk_mul_f32 v[36:37], v[126:127], v[20:21] op_sel_hi:[1,0]
	v_pk_mul_f32 v[244:245], v[70:71], v[70:71]
	v_pk_fma_f32 v[56:57], v[178:179], v[36:37], v[158:159] neg_lo:[1,0,0] neg_hi:[1,0,0]
	v_pk_mul_f32 v[36:37], v[124:125], v[20:21] op_sel_hi:[1,0]
	v_pk_mul_f32 v[242:243], v[68:69], v[68:69]
	v_pk_fma_f32 v[58:59], v[178:179], v[36:37], v[156:157] neg_lo:[1,0,0] neg_hi:[1,0,0]
	v_pk_mul_f32 v[36:37], v[98:99], v[20:21] op_sel_hi:[1,0]
	v_pk_mul_f32 v[248:249], v[66:67], v[66:67]
	v_pk_fma_f32 v[52:53], v[178:179], v[36:37], v[162:163] neg_lo:[1,0,0] neg_hi:[1,0,0]
	v_pk_mul_f32 v[36:37], v[96:97], v[20:21] op_sel_hi:[1,0]
	v_pk_mul_f32 v[246:247], v[64:65], v[64:65]
	v_pk_fma_f32 v[54:55], v[178:179], v[36:37], v[160:161] neg_lo:[1,0,0] neg_hi:[1,0,0]
	v_pk_mul_f32 v[36:37], v[102:103], v[20:21] op_sel_hi:[1,0]
	v_pk_mul_f32 v[252:253], v[62:63], v[62:63]
	v_pk_fma_f32 v[48:49], v[178:179], v[36:37], v[166:167] neg_lo:[1,0,0] neg_hi:[1,0,0]
	v_pk_mul_f32 v[36:37], v[100:101], v[20:21] op_sel_hi:[1,0]
	v_pk_mul_f32 v[250:251], v[60:61], v[60:61]
	v_pk_fma_f32 v[50:51], v[178:179], v[36:37], v[164:165] neg_lo:[1,0,0] neg_hi:[1,0,0]
	v_pk_mul_f32 v[36:37], v[106:107], v[20:21] op_sel_hi:[1,0]
	v_pk_mul_f32 v[156:157], v[58:59], v[58:59]
	v_pk_fma_f32 v[44:45], v[178:179], v[36:37], v[170:171] neg_lo:[1,0,0] neg_hi:[1,0,0]
	v_pk_mul_f32 v[36:37], v[104:105], v[20:21] op_sel_hi:[1,0]
	v_pk_mul_f32 v[158:159], v[56:57], v[56:57]
	v_pk_fma_f32 v[46:47], v[178:179], v[36:37], v[168:169] neg_lo:[1,0,0] neg_hi:[1,0,0]
	v_pk_mul_f32 v[36:37], v[110:111], v[20:21] op_sel_hi:[1,0]
	v_add_f32_e32 v156, v156, v157
	v_pk_fma_f32 v[38:39], v[178:179], v[36:37], v[192:193] neg_lo:[1,0,0] neg_hi:[1,0,0]
	v_pk_mul_f32 v[36:37], v[108:109], v[20:21] op_sel_hi:[1,0]
	v_pk_mul_f32 v[160:161], v[54:55], v[54:55]
	v_pk_fma_f32 v[42:43], v[178:179], v[36:37], v[30:31] neg_lo:[1,0,0] neg_hi:[1,0,0]
	v_mov_b32_e32 v37, v39
	v_mov_b32_e32 v36, v43
	v_mov_b32_e32 v30, v42
	v_mov_b32_e32 v31, v38
	v_pk_mul_f32 v[36:37], v[36:37], v[36:37]
	v_pk_mul_f32 v[162:163], v[52:53], v[52:53]
	v_pk_fma_f32 v[192:193], v[30:31], v[30:31], v[36:37]
	v_pk_mul_f32 v[30:31], v[82:83], v[20:21] op_sel_hi:[1,0]
	v_pk_mul_f32 v[164:165], v[50:51], v[50:51]
	v_pk_fma_f32 v[36:37], v[178:179], v[30:31], v[222:223] neg_lo:[1,0,0] neg_hi:[1,0,0]
	v_pk_mul_f32 v[30:31], v[80:81], v[20:21] op_sel_hi:[1,0]
	v_pk_mul_f32 v[222:223], v[84:85], v[20:21] op_sel_hi:[1,0]
	v_pk_fma_f32 v[40:41], v[178:179], v[30:31], v[196:197] neg_lo:[1,0,0] neg_hi:[1,0,0]
	v_mov_b32_e32 v197, v37
	v_mov_b32_e32 v196, v41
	v_mov_b32_e32 v30, v40
	v_mov_b32_e32 v31, v36
	v_pk_mul_f32 v[196:197], v[196:197], v[196:197]
	v_pk_fma_f32 v[34:35], v[178:179], v[222:223], v[34:35] neg_lo:[1,0,0] neg_hi:[1,0,0]
	v_pk_fma_f32 v[196:197], v[30:31], v[30:31], v[196:197]
	v_pk_mul_f32 v[30:31], v[86:87], v[20:21] op_sel_hi:[1,0]
	v_mov_b32_e32 v222, v34
	v_pk_fma_f32 v[30:31], v[178:179], v[30:31], v[224:225] neg_lo:[1,0,0] neg_hi:[1,0,0]
	v_mov_b32_e32 v224, v35
	v_mov_b32_e32 v225, v31
	v_mov_b32_e32 v223, v30
	v_pk_mul_f32 v[224:225], v[224:225], v[224:225]
	v_add_f32_e32 v21, v232, v233
	v_pk_fma_f32 v[222:223], v[222:223], v[222:223], v[224:225]
	v_add_f32_e32 v224, v228, v229
	v_add_f32_e32 v173, v224, v173
	v_add_f32_e32 v21, v173, v21
	v_add_f32_e32 v173, v230, v231
	v_add_f32_e32 v21, v21, v173
	v_add_f32_e32 v173, v236, v237
	v_add_f32_e32 v21, v21, v173
	v_add_f32_e32 v173, v234, v235
	v_add_f32_e32 v21, v21, v173
	v_add_f32_e32 v173, v240, v241
	v_add_f32_e32 v21, v21, v173
	v_add_f32_e32 v173, v238, v239
	v_add_f32_e32 v21, v21, v173
	v_add_f32_e32 v173, v244, v245
	v_add_f32_e32 v21, v21, v173
	v_add_f32_e32 v173, v242, v243
	v_add_f32_e32 v21, v21, v173
	v_add_f32_e32 v173, v248, v249
	v_add_f32_e32 v21, v21, v173
	v_add_f32_e32 v173, v246, v247
	v_add_f32_e32 v21, v21, v173
	v_add_f32_e32 v173, v252, v253
	v_add_f32_e32 v21, v21, v173
	v_add_f32_e32 v173, v250, v251
	v_add_f32_e32 v21, v21, v173
	v_add_f32_e32 v21, v21, v156
	v_add_f32_e32 v156, v158, v159
	v_add_f32_e32 v21, v21, v156
	v_add_f32_e32 v156, v160, v161
	v_add_f32_e32 v21, v21, v156
	v_add_f32_e32 v156, v162, v163
	v_pk_mul_f32 v[166:167], v[48:49], v[48:49]
	v_add_f32_e32 v21, v21, v156
	v_add_f32_e32 v156, v164, v165
	v_pk_mul_f32 v[168:169], v[46:47], v[46:47]
	v_add_f32_e32 v21, v21, v156
	v_add_f32_e32 v156, v166, v167
	v_pk_mul_f32 v[170:171], v[44:45], v[44:45]
	v_add_f32_e32 v21, v21, v156
	v_add_f32_e32 v156, v168, v169
	v_add_f32_e32 v21, v21, v156
	v_add_f32_e32 v156, v170, v171
	v_add_f32_e32 v21, v21, v156
	v_add_f32_e32 v21, v21, v192
	v_add_f32_e32 v21, v21, v193
	v_add_f32_e32 v21, v21, v196
	v_add_f32_e32 v21, v21, v197
	v_add_f32_e32 v21, v21, v222
	v_add_f32_e32 v21, v21, v223
	v_add_f32_e32 v21, v21, v32
	v_add_f32_e32 v21, v21, v33
	v_add_f32_e32 v21, v21, v150
	v_add_f32_e32 v21, v21, v151
	ds_bpermute_b32 v32, v221, v21
	s_mov_b32 s6, 0x800000
	global_load_dwordx2 v[80:81], v[188:189], off offset:16
	global_load_dwordx4 v[112:115], v[186:187], off offset:32
	global_load_dwordx4 v[116:119], v[186:187], off offset:64
	global_load_dwordx2 v[82:83], v[188:189], off offset:32
	global_load_dwordx2 v[84:85], v[188:189], off offset:48
	global_load_dwordx4 v[120:123], v[186:187], off offset:96
	global_load_dwordx4 v[124:127], v[186:187], off offset:128
	global_load_dwordx2 v[86:87], v[188:189], off offset:64
	global_load_dwordx2 v[88:89], v[188:189], off offset:80
	global_load_dwordx4 v[128:131], v[186:187], off offset:160
	global_load_dwordx4 v[132:135], v[186:187], off offset:192
	global_load_dwordx2 v[90:91], v[188:189], off offset:96
	global_load_dwordx2 v[92:93], v[188:189], off offset:112
	global_load_dwordx4 v[136:139], v[186:187], off offset:224
	global_load_dwordx4 v[140:143], v[186:187], off offset:256
	global_load_dwordx2 v[94:95], v[188:189], off offset:128
	global_load_dwordx2 v[96:97], v[188:189], off offset:144
	global_load_dwordx4 v[158:161], v[186:187], off offset:288
	global_load_dwordx4 v[162:165], v[186:187], off offset:320
	global_load_dwordx2 v[98:99], v[188:189], off offset:160
	global_load_dwordx2 v[100:101], v[188:189], off offset:176
	global_load_dwordx4 v[166:169], v[186:187], off offset:352
	global_load_dwordx4 v[108:111], v[186:187], off offset:384
	global_load_dwordx2 v[102:103], v[188:189], off offset:192
	global_load_dwordx2 v[104:105], v[188:189], off offset:208
	global_load_dwordx2 v[106:107], v[188:189], off offset:224
	global_load_dwordx2 v[170:171], v[188:189], off offset:240
	global_load_dwordx4 v[222:225], v[186:187], off offset:416
	global_load_dwordx4 v[226:229], v[186:187], off offset:448
	global_load_dwordx4 v[230:233], v[186:187], off offset:480
	v_mbcnt_lo_u32_b32 v250, -1, 0
	v_mbcnt_hi_u32_b32 v250, -1, v250
	v_and_b32_e32 v250, 32, v250
	v_lshrrev_b32_e32 v250, 2, v250
	v_mov_b32_e32 v251, 0
	v_lshl_add_u64 v[252:253], v[190:191], 0, v[250:251]
	s_waitcnt vmcnt(30)
	v_lshlrev_b32_e32 v156, 16, v78
	v_and_b32_e32 v157, 0xffff0000, v78
	v_lshlrev_b32_e32 v78, 16, v79
	s_waitcnt lgkmcnt(0)
	v_add_f32_e32 v21, v21, v32
	v_fmamk_f32 v21, v21, 0x3c000000, v195
	v_mul_f32_e32 v32, 0x4b800000, v21
	v_cmp_gt_f32_e32 vcc, s6, v21
	v_and_b32_e32 v79, 0xffff0000, v79
	v_cndmask_b32_e32 v21, v21, v32, vcc
	v_rsq_f32_e32 v21, v21
	s_nop 0
	v_mul_f32_e32 v32, 0x45800000, v21
	v_cndmask_b32_e32 v21, v21, v32, vcc
	v_mul_f32_e32 v32, v207, v21
	v_pk_mul_f32 v[148:149], v[148:149], v[32:33] op_sel_hi:[1,0]
	v_pk_mul_f32 v[76:77], v[76:77], v[32:33] op_sel_hi:[1,0]
	v_pk_mul_f32 v[16:17], v[16:17], v[148:149]
	v_pk_mul_f32 v[18:19], v[18:19], v[76:77]
	v_pk_mul_f32 v[16:17], v[16:17], v[156:157]
	v_pk_mul_f32 v[18:19], v[18:19], v[78:79]
	v_cvt_pk_bf16_f32 v236, v16, v17
	v_cvt_pk_bf16_f32 v237, v18, v19
	v_pk_mul_f32 v[148:149], v[152:153], v[32:33] op_sel_hi:[1,0]
	v_pk_mul_f32 v[74:75], v[74:75], v[32:33] op_sel_hi:[1,0]
	v_pk_mul_f32 v[72:73], v[72:73], v[32:33] op_sel_hi:[1,0]
	v_pk_mul_f32 v[70:71], v[70:71], v[32:33] op_sel_hi:[1,0]
	v_pk_mul_f32 v[68:69], v[68:69], v[32:33] op_sel_hi:[1,0]
	v_pk_mul_f32 v[66:67], v[66:67], v[32:33] op_sel_hi:[1,0]
	v_pk_mul_f32 v[64:65], v[64:65], v[32:33] op_sel_hi:[1,0]
	v_pk_mul_f32 v[62:63], v[62:63], v[32:33] op_sel_hi:[1,0]
	v_pk_mul_f32 v[60:61], v[60:61], v[32:33] op_sel_hi:[1,0]
	v_pk_mul_f32 v[58:59], v[58:59], v[32:33] op_sel_hi:[1,0]
	v_pk_mul_f32 v[56:57], v[56:57], v[32:33] op_sel_hi:[1,0]
	v_pk_mul_f32 v[54:55], v[54:55], v[32:33] op_sel_hi:[1,0]
	v_pk_mul_f32 v[52:53], v[52:53], v[32:33] op_sel_hi:[1,0]
	v_pk_mul_f32 v[50:51], v[50:51], v[32:33] op_sel_hi:[1,0]
	v_pk_mul_f32 v[48:49], v[48:49], v[32:33] op_sel_hi:[1,0]
	v_pk_mul_f32 v[46:47], v[46:47], v[32:33] op_sel_hi:[1,0]
	v_pk_mul_f32 v[44:45], v[44:45], v[32:33] op_sel_hi:[1,0]
	v_pk_mul_f32 v[42:43], v[42:43], v[32:33] op_sel_hi:[1,0]
	v_pk_mul_f32 v[38:39], v[38:39], v[32:33] op_sel_hi:[1,0]
	v_pk_mul_f32 v[40:41], v[40:41], v[32:33] op_sel_hi:[1,0]
	v_pk_mul_f32 v[36:37], v[36:37], v[32:33] op_sel_hi:[1,0]
	v_pk_mul_f32 v[34:35], v[34:35], v[32:33] op_sel_hi:[1,0]
	v_pk_mul_f32 v[30:31], v[30:31], v[32:33] op_sel_hi:[1,0]
	s_waitcnt vmcnt(29)
	v_lshlrev_b32_e32 v76, 16, v80
	v_and_b32_e32 v77, 0xffff0000, v80
	v_lshlrev_b32_e32 v78, 16, v81
	v_and_b32_e32 v79, 0xffff0000, v81
	s_waitcnt vmcnt(28)
	v_pk_mul_f32 v[16:17], v[112:113], v[148:149]
	s_nop 0
	v_pk_mul_f32 v[16:17], v[16:17], v[76:77]
	v_pk_mul_f32 v[76:77], v[146:147], v[32:33] op_sel_hi:[1,0]
	v_cvt_pk_bf16_f32 v238, v16, v17
	v_pk_mul_f32 v[18:19], v[114:115], v[76:77]
	s_nop 0
	v_pk_mul_f32 v[18:19], v[18:19], v[78:79]
	v_pk_mul_f32 v[78:79], v[154:155], v[32:33] op_sel_hi:[1,0]
	v_cvt_pk_bf16_f32 v239, v18, v19
	s_nop 1
	v_permlane32_swap_b32 v236, v238
	v_permlane32_swap_b32 v237, v239
	global_store_dwordx4 v[252:253], v[236:239], off
	s_waitcnt vmcnt(28)
	v_pk_mul_f32 v[16:17], v[116:117], v[78:79]
	s_waitcnt vmcnt(27)
	v_lshlrev_b32_e32 v146, 16, v82
	v_and_b32_e32 v147, 0xffff0000, v82
	v_pk_mul_f32 v[18:19], v[118:119], v[74:75]
	v_lshlrev_b32_e32 v74, 16, v83
	v_and_b32_e32 v75, 0xffff0000, v83
	v_pk_mul_f32 v[16:17], v[16:17], v[146:147]
	v_pk_mul_f32 v[18:19], v[18:19], v[74:75]
	v_cvt_pk_bf16_f32 v236, v16, v17
	v_cvt_pk_bf16_f32 v237, v18, v19
	v_pk_mul_f32 v[74:75], v[144:145], v[32:33] op_sel_hi:[1,0]
	s_waitcnt vmcnt(26)
	v_lshlrev_b32_e32 v76, 16, v84
	v_and_b32_e32 v77, 0xffff0000, v84
	v_lshlrev_b32_e32 v78, 16, v85
	v_and_b32_e32 v79, 0xffff0000, v85
	s_waitcnt vmcnt(25)
	v_pk_mul_f32 v[16:17], v[120:121], v[74:75]
	v_pk_mul_f32 v[18:19], v[122:123], v[72:73]
	v_pk_mul_f32 v[16:17], v[16:17], v[76:77]
	v_pk_mul_f32 v[18:19], v[18:19], v[78:79]
	v_cvt_pk_bf16_f32 v238, v16, v17
	v_cvt_pk_bf16_f32 v239, v18, v19
	s_nop 1
	v_permlane32_swap_b32 v236, v238
	v_permlane32_swap_b32 v237, v239
	global_store_dwordx4 v[252:253], v[236:239], off offset:32
	s_waitcnt vmcnt(25)
	v_pk_mul_f32 v[16:17], v[70:71], v[124:125]
	s_waitcnt vmcnt(24)
	v_lshlrev_b32_e32 v70, 16, v86
	v_and_b32_e32 v71, 0xffff0000, v86
	v_pk_mul_f32 v[18:19], v[68:69], v[126:127]
	v_lshlrev_b32_e32 v68, 16, v87
	v_and_b32_e32 v69, 0xffff0000, v87
	v_pk_mul_f32 v[16:17], v[16:17], v[70:71]
	v_pk_mul_f32 v[18:19], v[18:19], v[68:69]
	v_cvt_pk_bf16_f32 v236, v16, v17
	v_cvt_pk_bf16_f32 v237, v18, v19
	s_waitcnt vmcnt(23)
	v_lshlrev_b32_e32 v68, 16, v88
	v_and_b32_e32 v69, 0xffff0000, v88
	v_lshlrev_b32_e32 v70, 16, v89
	v_and_b32_e32 v71, 0xffff0000, v89
	s_waitcnt vmcnt(22)
	v_pk_mul_f32 v[16:17], v[66:67], v[128:129]
	v_pk_mul_f32 v[18:19], v[64:65], v[130:131]
	v_pk_mul_f32 v[16:17], v[16:17], v[68:69]
	v_pk_mul_f32 v[18:19], v[18:19], v[70:71]
	v_cvt_pk_bf16_f32 v238, v16, v17
	v_cvt_pk_bf16_f32 v239, v18, v19
	s_nop 1
	v_permlane32_swap_b32 v236, v238
	v_permlane32_swap_b32 v237, v239
	global_store_dwordx4 v[252:253], v[236:239], off offset:64
	s_waitcnt vmcnt(22)
	v_pk_mul_f32 v[16:17], v[62:63], v[132:133]
	s_waitcnt vmcnt(21)
	v_lshlrev_b32_e32 v62, 16, v90
	v_and_b32_e32 v63, 0xffff0000, v90
	v_pk_mul_f32 v[18:19], v[60:61], v[134:135]
	v_lshlrev_b32_e32 v60, 16, v91
	v_and_b32_e32 v61, 0xffff0000, v91
	v_pk_mul_f32 v[16:17], v[16:17], v[62:63]
	v_pk_mul_f32 v[18:19], v[18:19], v[60:61]
	v_cvt_pk_bf16_f32 v236, v16, v17
	v_cvt_pk_bf16_f32 v237, v18, v19
	s_waitcnt vmcnt(20)
	v_lshlrev_b32_e32 v60, 16, v92
	v_and_b32_e32 v61, 0xffff0000, v92
	v_lshlrev_b32_e32 v62, 16, v93
	v_and_b32_e32 v63, 0xffff0000, v93
	s_waitcnt vmcnt(19)
	v_pk_mul_f32 v[16:17], v[58:59], v[136:137]
	v_pk_mul_f32 v[18:19], v[56:57], v[138:139]
	v_pk_mul_f32 v[16:17], v[16:17], v[60:61]
	v_pk_mul_f32 v[18:19], v[18:19], v[62:63]
	v_cvt_pk_bf16_f32 v238, v16, v17
	v_cvt_pk_bf16_f32 v239, v18, v19
	s_nop 1
	v_permlane32_swap_b32 v236, v238
	v_permlane32_swap_b32 v237, v239
	global_store_dwordx4 v[252:253], v[236:239], off offset:96
	s_waitcnt vmcnt(19)
	v_pk_mul_f32 v[16:17], v[54:55], v[140:141]
	s_waitcnt vmcnt(18)
	v_lshlrev_b32_e32 v54, 16, v94
	v_and_b32_e32 v55, 0xffff0000, v94
	v_pk_mul_f32 v[18:19], v[52:53], v[142:143]
	v_lshlrev_b32_e32 v52, 16, v95
	v_and_b32_e32 v53, 0xffff0000, v95
	v_pk_mul_f32 v[16:17], v[16:17], v[54:55]
	v_pk_mul_f32 v[18:19], v[18:19], v[52:53]
	v_cvt_pk_bf16_f32 v236, v16, v17
	v_cvt_pk_bf16_f32 v237, v18, v19
	s_waitcnt vmcnt(17)
	v_lshlrev_b32_e32 v52, 16, v96
	v_and_b32_e32 v53, 0xffff0000, v96
	v_lshlrev_b32_e32 v54, 16, v97
	v_and_b32_e32 v55, 0xffff0000, v97
	s_waitcnt vmcnt(16)
	v_pk_mul_f32 v[16:17], v[50:51], v[158:159]
	v_pk_mul_f32 v[18:19], v[48:49], v[160:161]
	v_pk_mul_f32 v[16:17], v[16:17], v[52:53]
	v_pk_mul_f32 v[18:19], v[18:19], v[54:55]
	v_cvt_pk_bf16_f32 v238, v16, v17
	v_cvt_pk_bf16_f32 v239, v18, v19
	s_nop 1
	v_permlane32_swap_b32 v236, v238
	v_permlane32_swap_b32 v237, v239
	global_store_dwordx4 v[252:253], v[236:239], off offset:128
	s_waitcnt vmcnt(16)
	v_pk_mul_f32 v[16:17], v[46:47], v[162:163]
	s_waitcnt vmcnt(15)
	v_lshlrev_b32_e32 v46, 16, v98
	v_and_b32_e32 v47, 0xffff0000, v98
	v_pk_mul_f32 v[18:19], v[44:45], v[164:165]
	v_lshlrev_b32_e32 v44, 16, v99
	v_and_b32_e32 v45, 0xffff0000, v99
	v_pk_mul_f32 v[16:17], v[16:17], v[46:47]
	v_pk_mul_f32 v[18:19], v[18:19], v[44:45]
	v_cvt_pk_bf16_f32 v236, v16, v17
	v_cvt_pk_bf16_f32 v237, v18, v19
	s_waitcnt vmcnt(14)
	v_lshlrev_b32_e32 v44, 16, v100
	v_and_b32_e32 v45, 0xffff0000, v100
	v_lshlrev_b32_e32 v46, 16, v101
	v_and_b32_e32 v47, 0xffff0000, v101
	s_waitcnt vmcnt(13)
	v_pk_mul_f32 v[16:17], v[42:43], v[166:167]
	v_pk_mul_f32 v[18:19], v[38:39], v[168:169]
	v_pk_mul_f32 v[16:17], v[16:17], v[44:45]
	v_pk_mul_f32 v[18:19], v[18:19], v[46:47]
	v_cvt_pk_bf16_f32 v238, v16, v17
	v_cvt_pk_bf16_f32 v239, v18, v19
	s_nop 1
	v_permlane32_swap_b32 v236, v238
	v_permlane32_swap_b32 v237, v239
	global_store_dwordx4 v[252:253], v[236:239], off offset:160
	s_waitcnt vmcnt(13)
	v_pk_mul_f32 v[16:17], v[40:41], v[108:109]
	s_waitcnt vmcnt(12)
	v_lshlrev_b32_e32 v40, 16, v102
	v_and_b32_e32 v41, 0xffff0000, v102
	v_pk_mul_f32 v[18:19], v[36:37], v[110:111]
	v_lshlrev_b32_e32 v36, 16, v103
	v_and_b32_e32 v37, 0xffff0000, v103
	v_pk_mul_f32 v[16:17], v[16:17], v[40:41]
	v_pk_mul_f32 v[18:19], v[18:19], v[36:37]
	v_cvt_pk_bf16_f32 v236, v16, v17
	v_cvt_pk_bf16_f32 v237, v18, v19
	s_waitcnt vmcnt(11)
	v_lshlrev_b32_e32 v36, 16, v104
	v_and_b32_e32 v37, 0xffff0000, v104
	v_lshlrev_b32_e32 v38, 16, v105
	v_and_b32_e32 v39, 0xffff0000, v105
	s_waitcnt vmcnt(8)
	v_pk_mul_f32 v[16:17], v[34:35], v[222:223]
	v_pk_mul_f32 v[18:19], v[30:31], v[224:225]
	v_pk_mul_f32 v[16:17], v[16:17], v[36:37]
	v_pk_mul_f32 v[18:19], v[18:19], v[38:39]
	v_cvt_pk_bf16_f32 v238, v16, v17
	v_cvt_pk_bf16_f32 v239, v18, v19
	s_nop 1
	v_permlane32_swap_b32 v236, v238
	v_permlane32_swap_b32 v237, v239
	global_store_dwordx4 v[252:253], v[236:239], off offset:192
	v_mov_b32_e32 v34, v26
	v_mov_b32_e32 v35, v28
	v_mov_b32_e32 v28, v27
	v_pk_mul_f32 v[26:27], v[34:35], v[32:33] op_sel_hi:[1,0]
	v_pk_mul_f32 v[28:29], v[28:29], v[32:33] op_sel_hi:[1,0]
	s_waitcnt vmcnt(8)
	v_pk_mul_f32 v[16:17], v[26:27], v[226:227]
	v_lshlrev_b32_e32 v26, 16, v106
	v_and_b32_e32 v27, 0xffff0000, v106
	v_pk_mul_f32 v[18:19], v[28:29], v[228:229]
	v_lshlrev_b32_e32 v28, 16, v107
	v_and_b32_e32 v29, 0xffff0000, v107
	v_pk_mul_f32 v[16:17], v[16:17], v[26:27]
	v_pk_mul_f32 v[18:19], v[18:19], v[28:29]
	v_cvt_pk_bf16_f32 v236, v16, v17
	v_cvt_pk_bf16_f32 v237, v18, v19
	v_mov_b32_e32 v26, v22
	v_mov_b32_e32 v27, v24
	v_mov_b32_e32 v24, v23
	v_pk_mul_f32 v[22:23], v[26:27], v[32:33] op_sel_hi:[1,0]
	v_pk_mul_f32 v[24:25], v[24:25], v[32:33] op_sel_hi:[1,0]
	v_lshlrev_b32_e32 v26, 16, v170
	v_and_b32_e32 v27, 0xffff0000, v170
	v_lshlrev_b32_e32 v28, 16, v171
	v_and_b32_e32 v29, 0xffff0000, v171
	s_waitcnt vmcnt(7)
	v_pk_mul_f32 v[16:17], v[22:23], v[230:231]
	v_pk_mul_f32 v[18:19], v[24:25], v[232:233]
	v_pk_mul_f32 v[16:17], v[16:17], v[26:27]
	v_pk_mul_f32 v[18:19], v[18:19], v[28:29]
	v_cvt_pk_bf16_f32 v238, v16, v17
	v_cvt_pk_bf16_f32 v239, v18, v19
	s_nop 1
	v_permlane32_swap_b32 v236, v238
	v_permlane32_swap_b32 v237, v239
	global_store_dwordx4 v[252:253], v[236:239], off offset:224
	s_cbranch_execnz .LBB0_532
	s_branch .LBB0_565
